# DeltaNet gate stage: a_log load hoisted (one round trip less per item); attention item: norm-weight load no longer serialised in front of the row loads
# speedup vs baseline: 1.0094x; 1.0006x over previous
.LBB0_310:
	s_and_b64 vcc, exec, s[0:1]
	s_cbranch_vccz .LBB0_275
	v_mov_b32_e32 v45, v154
	s_lshl_b32 s0, s26, 6
	s_ashr_i32 s6, s26, 8
	v_and_b32_e32 v96, 63, v45
	s_and_b32 s10, s0, 0x7c0
	v_cmp_lt_u32_sdwa s[4:5], v45, v252 src0_sel:BYTE_0 src1_sel:DWORD
	s_and_saveexec_b64 s[0:1], s[4:5]
	s_cbranch_execz .LBB0_316
	s_ashr_i32 s7, s6, 31
	s_lshl_b64 s[4:5], s[6:7], 11
	s_or_b32 s4, s4, s10
	v_or_b32_e32 v0, s4, v96
	v_mov_b32_e32 v1, s5
	v_readlane_b32 s4, v253, 61
	s_bfe_u32 s8, s26, 0x30005
	v_lshlrev_b64 v[0:1], 6, v[0:1]
	v_readlane_b32 s5, v253, 62
	v_readlane_b32 s36, v253, 27
	v_readlane_b32 s46, v253, 37
	v_lshl_add_u64 v[0:1], s[4:5], 0, v[0:1]
	s_lshl_b32 s4, s8, 2
	s_mov_b32 s5, s52
	v_lshl_add_u64 v[0:1], v[0:1], 0, s[4:5]
	v_readlane_b32 s4, v254, 62
	s_or_b32 s4, s8, s4
	s_lshl_b64 s[4:5], s[4:5], 2
	v_readlane_b32 s47, v253, 38
	s_add_u32 s8, s46, s4
	s_addc_u32 s9, s47, s5
	global_load_dword v2, v[0:1], off
	s_nop 0
	global_load_dword v0, v[0:1], off offset:32
	s_mov_b32 s7, 0x41a00000
	global_load_dword v1, v137, s[8:9]
	v_readlane_b32 s14, v253, 35
	v_readlane_b32 s15, v253, 36
	s_add_u32 s14, s14, s4
	s_addc_u32 s15, s15, s5
	global_load_dword v16, v137, s[14:15]
	v_readlane_b32 s37, v253, 28
	v_readlane_b32 s38, v253, 29
	v_readlane_b32 s39, v253, 30
	v_readlane_b32 s40, v253, 31
	v_readlane_b32 s41, v253, 32
	v_readlane_b32 s42, v253, 33
	v_readlane_b32 s43, v253, 34
	v_readlane_b32 s44, v253, 35
	v_readlane_b32 s45, v253, 36
	v_readlane_b32 s48, v253, 39
	v_readlane_b32 s49, v253, 40
	v_readlane_b32 s50, v253, 41
	v_readlane_b32 s51, v253, 42
	s_waitcnt vmcnt(0)
	v_add_f32_e32 v1, v2, v1
	v_cmp_nlt_f32_e32 vcc, s7, v1
	s_and_saveexec_b64 s[8:9], vcc
	s_cbranch_execz .LBB0_314
	v_mul_f32_e32 v1, 0x3fb8aa3b, v1
	v_exp_f32_e32 v1, v1
	s_mov_b32 s7, 0x3f2aaaab
	v_add_f32_e32 v4, 1.0, v1
	v_frexp_mant_f32_e32 v6, v4
	v_cvt_f64_f32_e32 v[2:3], v4
	v_frexp_exp_i32_f64_e32 v2, v[2:3]
	v_cmp_gt_f32_e32 vcc, s7, v6
	v_add_f32_e32 v5, -1.0, v4
	v_sub_f32_e32 v7, v5, v4
	v_subbrev_co_u32_e32 v10, vcc, 0, v2, vcc
	v_sub_u32_e32 v2, 0, v10
	v_sub_f32_e32 v5, v1, v5
	v_add_f32_e32 v7, 1.0, v7
	v_ldexp_f32 v3, v4, v2
	v_add_f32_e32 v5, v5, v7
	v_add_f32_e32 v4, -1.0, v3
	v_add_f32_e32 v6, 1.0, v3
	v_ldexp_f32 v2, v5, v2
	v_add_f32_e32 v5, 1.0, v4
	v_add_f32_e32 v7, -1.0, v6
	v_sub_f32_e32 v5, v3, v5
	v_sub_f32_e32 v3, v3, v7
	v_add_f32_e32 v5, v2, v5
	v_add_f32_e32 v2, v2, v3
	v_add_f32_e32 v11, v6, v2
	v_rcp_f32_e32 v13, v11
	v_sub_f32_e32 v3, v11, v6
	v_sub_f32_e32 v12, v2, v3
	v_add_f32_e32 v3, v4, v5
	v_mul_f32_e32 v15, v3, v13
	v_sub_f32_e32 v2, v3, v4
	v_mul_f32_e32 v4, v11, v15
	v_fma_f32 v6, v15, v11, -v4
	v_fmac_f32_e32 v6, v15, v12
	v_sub_f32_e32 v14, v5, v2
	v_add_f32_e32 v2, v4, v6
	v_sub_f32_e32 v5, v3, v2
	v_pk_add_f32 v[8:9], v[2:3], v[4:5] neg_lo:[0,1] neg_hi:[0,1]
	v_mov_b32_e32 v7, v2
	v_pk_add_f32 v[2:3], v[8:9], v[6:7] neg_lo:[0,1] neg_hi:[0,1]
	s_mov_b32 s7, 0x3f317218
	v_add_f32_e32 v3, v14, v3
	v_add_f32_e32 v2, v2, v3
	v_add_f32_e32 v3, v5, v2
	v_mul_f32_e32 v14, v13, v3
	v_mul_f32_e32 v4, v11, v14
	v_fma_f32 v6, v14, v11, -v4
	v_fmac_f32_e32 v6, v14, v12
	v_sub_f32_e32 v5, v5, v3
	v_add_f32_e32 v11, v2, v5
	v_add_f32_e32 v2, v4, v6
	v_sub_f32_e32 v5, v3, v2
	v_pk_add_f32 v[8:9], v[2:3], v[4:5] neg_lo:[0,1] neg_hi:[0,1]
	v_mov_b32_e32 v7, v2
	v_pk_add_f32 v[2:3], v[8:9], v[6:7] neg_lo:[0,1] neg_hi:[0,1]
	s_nop 0
	v_add_f32_e32 v3, v11, v3
	v_add_f32_e32 v2, v2, v3
	v_add_f32_e32 v3, v15, v14
	v_add_f32_e32 v2, v5, v2
	v_sub_f32_e32 v4, v3, v15
	v_mul_f32_e32 v2, v13, v2
	v_sub_f32_e32 v4, v14, v4
	v_add_f32_e32 v4, v4, v2
	v_add_f32_e32 v6, v3, v4
	v_mul_f32_e32 v7, v6, v6
	v_mov_b32_e32 v2, 0x3ecc95a3
	v_fmamk_f32 v2, v7, 0x3e9b6dac, v2
	v_fmaak_f32 v139, v7, v2, 0x3f2aaada
	v_cvt_f32_i32_e32 v2, v10
	v_sub_f32_e32 v3, v6, v3
	v_sub_f32_e32 v3, v4, v3
	v_ldexp_f32 v8, v3, 1
	v_mul_f32_e32 v3, v6, v7
	v_ldexp_f32 v5, v6, 1
	v_pk_mul_f32 v[6:7], v[2:3], v[138:139]
	s_nop 0
	v_fma_f32 v4, v2, s7, -v6
	v_fmac_f32_e32 v4, 0xb102e308, v2
	v_pk_add_f32 v[2:3], v[6:7], v[4:5]
	s_mov_b32 s7, 0x7f800000
	v_sub_f32_e32 v5, v3, v5
	v_sub_f32_e32 v5, v7, v5
	v_add_f32_e32 v9, v8, v5
	v_mov_b32_e32 v8, v6
	v_pk_add_f32 v[6:7], v[2:3], v[6:7] neg_lo:[0,1] neg_hi:[0,1]
	v_pk_add_f32 v[10:11], v[2:3], v[8:9]
	v_mov_b32_e32 v5, v2
	v_mov_b32_e32 v7, v11
	v_pk_add_f32 v[12:13], v[4:5], v[6:7] neg_lo:[0,1] neg_hi:[0,1]
	v_pk_add_f32 v[4:5], v[4:5], v[6:7]
	v_mov_b32_e32 v8, v9
	v_pk_add_f32 v[6:7], v[4:5], v[2:3] op_sel:[1,0] op_sel_hi:[0,1] neg_lo:[0,1] neg_hi:[0,1]
	v_pk_add_f32 v[14:15], v[10:11], v[6:7] op_sel_hi:[1,0] neg_lo:[0,1] neg_hi:[0,1]
	v_mov_b32_e32 v10, v11
	v_mov_b32_e32 v11, v5
	v_pk_mov_b32 v[6:7], v[2:3], v[6:7] op_sel:[1,0]
	v_mov_b32_e32 v9, v2
	v_pk_add_f32 v[6:7], v[10:11], v[6:7] neg_lo:[0,1] neg_hi:[0,1]
	v_mov_b32_e32 v14, v12
	v_pk_add_f32 v[2:3], v[8:9], v[6:7] neg_lo:[0,1] neg_hi:[0,1]
	v_mov_b32_e32 v13, v5
	v_pk_add_f32 v[6:7], v[14:15], v[2:3]
	v_cmp_neq_f32_e32 vcc, s7, v1
	v_pk_add_f32 v[8:9], v[6:7], v[6:7] op_sel:[0,1] op_sel_hi:[1,0]
	s_mov_b32 s7, 0x33800000
	v_pk_add_f32 v[4:5], v[4:5], v[8:9] op_sel:[1,0] op_sel_hi:[0,1]
	v_mov_b32_e32 v7, v4
	v_pk_add_f32 v[10:11], v[6:7], v[12:13] neg_lo:[0,1] neg_hi:[0,1]
	v_mov_b32_e32 v3, v8
	v_sub_f32_e32 v5, v6, v10
	v_pk_add_f32 v[2:3], v[2:3], v[10:11] neg_lo:[0,1] neg_hi:[0,1]
	v_sub_f32_e32 v5, v12, v5
	v_add_f32_e32 v2, v2, v5
	v_add_f32_e32 v2, v2, v3
	v_add_f32_e32 v2, v4, v2
	v_cndmask_b32_e32 v2, v250, v2, vcc
	v_cmp_ngt_f32_e32 vcc, -1.0, v1
	s_nop 1
	v_cndmask_b32_e32 v2, v251, v2, vcc
	v_cmp_neq_f32_e32 vcc, -1.0, v1
	s_nop 1
	v_cndmask_b32_e32 v2, v159, v2, vcc
	v_cmp_lt_f32_e64 vcc, |v1|, s7
	s_nop 1
	v_cndmask_b32_e32 v1, v2, v1, vcc
.LBB0_314:
	s_or_b64 exec, exec, s[8:9]
	v_readlane_b32 s36, v253, 27
	v_readlane_b32 s44, v253, 35
	v_readlane_b32 s45, v253, 36
	s_add_u32 s4, s44, s4
	s_addc_u32 s5, s45, s5
	s_nop 0
	v_lshlrev_b32_e32 v4, 2, v96
	v_add_u32_e32 v5, -4, v4
	v_cmp_eq_u32_e32 vcc, 0, v96
	v_mul_f32_e32 v0, 0xbfb8aa3b, v0
	v_exp_f32_e32 v0, v0
	v_readlane_b32 s37, v253, 28
	v_readlane_b32 s38, v253, 29
	v_readlane_b32 s39, v253, 30
	v_add_f32_e32 v0, 1.0, v0
	v_rcp_f32_e32 v0, v0
	v_readlane_b32 s40, v253, 31
	v_readlane_b32 s41, v253, 32
	v_readlane_b32 s42, v253, 33
	v_readlane_b32 s43, v253, 34
	v_readlane_b32 s46, v253, 37
	v_readlane_b32 s47, v253, 38
	v_readlane_b32 s48, v253, 39
	v_readlane_b32 s49, v253, 40
	v_readlane_b32 s50, v253, 41
	v_readlane_b32 s51, v253, 42
	s_waitcnt vmcnt(0)
	v_mul_f32_e32 v2, 0x3fb8aa3b, v16
	v_exp_f32_e32 v2, v2
	s_nop 0
	v_mul_f32_e64 v3, v1, -v2
	ds_bpermute_b32 v5, v5, v3
	s_waitcnt lgkmcnt(0)
	v_fma_f32 v1, v1, -v2, v5
	v_cndmask_b32_e32 v1, v1, v3, vcc
	v_add_u32_e32 v2, -8, v4
	ds_bpermute_b32 v2, v2, v1
	v_cmp_gt_u32_e32 vcc, 2, v96
	s_waitcnt lgkmcnt(0)
	v_add_f32_e32 v2, v1, v2
	v_cndmask_b32_e32 v1, v2, v1, vcc
	v_add_u32_e32 v2, -16, v4
	ds_bpermute_b32 v2, v2, v1
	v_cmp_gt_u32_e32 vcc, 4, v96
	s_waitcnt lgkmcnt(0)
	v_add_f32_e32 v2, v1, v2
	v_cndmask_b32_e32 v1, v2, v1, vcc
	v_subrev_u32_e32 v2, 32, v4
	ds_bpermute_b32 v2, v2, v1
	v_cmp_gt_u32_e32 vcc, 8, v96
	s_waitcnt lgkmcnt(0)
	v_add_f32_e32 v2, v1, v2
	v_cndmask_b32_e32 v1, v2, v1, vcc
	v_subrev_u32_e32 v2, 64, v4
	ds_bpermute_b32 v2, v2, v1
	v_cmp_gt_u32_e32 vcc, 16, v96
	s_waitcnt lgkmcnt(0)
	v_add_f32_e32 v2, v1, v2
	v_cndmask_b32_e32 v1, v2, v1, vcc
	v_add_u32_e32 v2, 0xffffff80, v4
	ds_bpermute_b32 v2, v2, v1
	v_cmp_gt_u32_e32 vcc, 32, v96
	s_waitcnt lgkmcnt(0)
	v_add_f32_e32 v2, v1, v2
	v_cndmask_b32_e32 v1, v2, v1, vcc
	v_add_u32_e32 v2, v125, v4
	ds_write_b32 v2, v1
	v_add_u32_e32 v2, v126, v4
	ds_write_b32 v2, v0
	v_mul_f32_e32 v0, 0x3fb8aa3b, v1
	v_exp_f32_e32 v0, v0
	v_add_u32_e32 v1, v127, v4
	v_cmp_eq_u32_e32 vcc, 63, v96
	ds_write_b32 v1, v0
	s_and_b64 exec, exec, vcc
	s_cbranch_execz .LBB0_316
	s_ashr_i32 s27, s26, 31
	s_lshl_b64 s[4:5], s[26:27], 2
	v_readlane_b32 s7, v254, 11
	s_add_u32 s4, s7, s4
	v_readlane_b32 s7, v254, 12
	s_addc_u32 s5, s7, s5
	global_store_dword v137, v0, s[4:5]

.LBB0_396:
	v_mov_b32_e32 v16, v154
	s_movk_i32 s0, 0x80
	v_and_b32_e32 v114, 0xff, v16
	v_cmp_gt_u32_e32 vcc, s0, v114
	s_and_saveexec_b64 s[0:1], vcc
	s_cbranch_execz .LBB0_398
	v_readlane_b32 s36, v253, 27
	v_or_b32_e32 v136, s12, v114
	v_readlane_b32 s38, v253, 29
	v_readlane_b32 s39, v253, 30
	v_readlane_b32 s40, v253, 31
	v_readlane_b32 s41, v253, 32
	v_lshl_add_u64 v[0:1], v[136:137], 2, s[38:39]
	v_add_u32_e32 v136, s12, v114
	s_movk_i32 s4, 0xff00
	v_lshl_add_u64 v[2:3], v[136:137], 2, s[40:41]
	s_mov_b32 s5, -1
	v_lshl_add_u64 v[2:3], v[2:3], 0, s[4:5]
	v_cmp_gt_u32_e32 vcc, 64, v114
	v_readlane_b32 s37, v253, 28
	v_readlane_b32 s42, v253, 33
	v_cndmask_b32_e32 v1, v3, v1, vcc
	v_cndmask_b32_e32 v0, v2, v0, vcc
	global_load_dword v100, v[0:1], off
	v_lshl_add_u32 v1, v114, 2, v122
	v_readlane_b32 s43, v253, 34
	v_readlane_b32 s44, v253, 35
	v_readlane_b32 s45, v253, 36
	v_readlane_b32 s46, v253, 37
	v_readlane_b32 s47, v253, 38
	v_readlane_b32 s48, v253, 39
	v_readlane_b32 s49, v253, 40
	v_readlane_b32 s50, v253, 41
	v_readlane_b32 s51, v253, 42
.LBB0_398:
	s_or_b64 exec, exec, s[0:1]
	s_ashr_i32 s1, s23, 6
	s_mul_hi_i32 s4, s1, 0x55555556
	s_lshr_b32 s5, s4, 31
	s_add_i32 s26, s4, s5
	s_mul_i32 s4, s26, 3
	s_and_b32 s0, s23, 15
	s_bfe_u32 s13, s23, 0x20004
	s_sub_i32 s82, s1, s4
	s_cmp_eq_u32 s82, 1
	s_cselect_b32 s1, 2, 4
	s_cmp_lg_u32 s82, 0
	s_cselect_b32 s27, s1, 0
	s_sub_i32 s4, 4, s27
	s_lshr_b32 s1, 16, s27
	s_lshr_b32 s83, s0, s4
	s_mul_i32 s1, s83, s1
	s_sub_i32 s14, s0, s1
	s_mul_i32 s0, s26, 9
	s_add_i32 s0, s0, s82
	s_lshl_b32 s0, s0, 13
	s_lshl_b32 s1, s13, 11
	s_or_b32 s0, s0, s1
	s_sub_i32 s1, 11, s27
	s_lshl_b32 s1, s83, s1
	s_add_i32 s0, s0, s1
	s_ashr_i32 s1, s0, 31
	s_lshl_b64 s[4:5], s[0:1], 7
	v_readlane_b32 s8, v253, 49
	v_readlane_b32 s9, v253, 50
	s_add_u32 s4, s8, s4
	s_addc_u32 s5, s9, s5
	s_add_i32 s6, s0, 0x6000
	s_ashr_i32 s7, s6, 31
	s_lshl_b64 s[6:7], s[6:7], 7
	s_add_u32 s6, s8, s6
	s_addc_u32 s7, s9, s7
	s_add_i32 s0, s0, 0xc000
	s_ashr_i32 s1, s0, 31
	s_lshl_b64 s[0:1], s[0:1], 7
	s_add_u32 s8, s8, s0
	s_addc_u32 s9, s9, s1
	s_lshl_b32 s0, s14, 7
	v_lshrrev_b32_e32 v118, 6, v114
	s_add_i32 s1, s0, 0xffffff80
	v_and_b32_e32 v124, 31, v16
	v_lshlrev_b32_e32 v125, 5, v118
	v_add_u32_e32 v0, s1, v114
	v_or3_b32 v116, v124, s0, v125
	v_max_i32_e32 v136, 0, v0
	v_lshlrev_b64 v[0:1], 7, v[136:137]
	v_ashrrev_i32_e32 v117, 31, v116
	v_bfe_u32 v123, v16, 5, 1
	v_lshl_add_u64 v[40:41], s[8:9], 0, v[0:1]
	v_lshlrev_b64 v[0:1], 7, v[116:117]
	v_lshl_add_u64 v[0:1], s[4:5], 0, v[0:1]
	v_lshlrev_b32_e32 v136, 4, v123
	v_add_u32_e32 v115, 32, v125
	v_lshl_add_u64 v[0:1], v[0:1], 0, v[136:137]
	s_cmp_gt_i32 s14, 0
	v_add_u32_e32 v17, s1, v115
	global_load_dwordx4 v[52:55], v[0:1], off
	global_load_dwordx4 v[56:59], v[0:1], off offset:32
	global_load_dwordx4 v[60:63], v[0:1], off offset:64
	global_load_dwordx4 v[42:45], v[0:1], off offset:96
	v_lshl_add_u64 v[30:31], s[6:7], 0, v[136:137]
	v_or3_b32 v0, v124, s1, v125
	s_cselect_b64 s[6:7], -1, 0
	v_or_b32_e32 v18, v17, v124
	v_cmp_lt_i32_e32 vcc, -1, v17
	v_cndmask_b32_e64 v0, 0, v0, s[6:7]
	v_ashrrev_i32_e32 v1, 31, v0
	v_cndmask_b32_e32 v18, 0, v18, vcc
	v_ashrrev_i32_e32 v19, 31, v18
	v_lshlrev_b64 v[0:1], 7, v[0:1]
	v_lshlrev_b64 v[18:19], 7, v[18:19]
	v_lshl_add_u64 v[12:13], v[30:31], 0, v[0:1]
	v_lshl_add_u64 v[32:33], v[30:31], 0, v[18:19]
	global_load_dwordx4 v[0:3], v[12:13], off
	global_load_dwordx4 v[4:7], v[12:13], off offset:32
	global_load_dwordx4 v[8:11], v[12:13], off offset:64
	s_nop 0
	global_load_dwordx4 v[12:15], v[12:13], off offset:96
	s_nop 0
	global_load_dwordx4 v[18:21], v[32:33], off
	global_load_dwordx4 v[22:25], v[32:33], off offset:32
	global_load_dwordx4 v[26:29], v[32:33], off offset:64
	global_load_dwordx4 v[48:51], v[32:33], off offset:96
	s_nop 0
	global_load_dwordx4 v[32:35], v[40:41], off
	global_load_dwordx4 v[36:39], v[40:41], off offset:16
	global_load_dwordx4 v[64:67], v[40:41], off offset:32
	global_load_dwordx4 v[68:71], v[40:41], off offset:48
	global_load_dwordx4 v[72:75], v[40:41], off offset:64
	global_load_dwordx4 v[76:79], v[40:41], off offset:80
	global_load_dwordx4 v[80:83], v[40:41], off offset:96
	global_load_dwordx4 v[84:87], v[40:41], off offset:112
	v_and_b32_e32 v117, 63, v16
	s_waitcnt vmcnt(0)
	s_movk_i32 s8, 0x80
	v_cmp_gt_u32_e32 vcc, s8, v114
	s_and_saveexec_b64 s[8:9], vcc
	v_lshl_add_u32 v101, v114, 2, v122
	ds_write_b32 v101, v100 offset:35840
	s_or_b64 exec, exec, s[8:9]
	v_lshlrev_b32_e32 v110, 16, v52
	v_and_b32_e32 v111, 0xffff0000, v52
	v_and_b32_e32 v16, 32, v16
	v_lshlrev_b32_e32 v106, 16, v53
	v_and_b32_e32 v107, 0xffff0000, v53
	v_pk_mul_f32 v[52:53], v[110:111], v[110:111]
	v_lshl_add_u32 v17, v114, 1, v122
	v_add_u32_e32 v119, v122, v16
	v_pk_mul_f32 v[142:143], v[106:107], v[106:107]
	v_add_f32_e32 v52, v52, v53
	ds_write_b16 v17, v32
	ds_write_b16_d16_hi v17, v32 offset:560
	ds_write_b16 v17, v33 offset:1120
	ds_write_b16_d16_hi v17, v33 offset:1680
	ds_write_b16 v17, v34 offset:4480
	ds_write_b16_d16_hi v17, v34 offset:5040
	ds_write_b16 v17, v35 offset:5600
	ds_write_b16_d16_hi v17, v35 offset:6160
	ds_write_b16 v17, v36 offset:8960
	ds_write_b16_d16_hi v17, v36 offset:9520
	ds_write_b16 v17, v37 offset:10080
	ds_write_b16_d16_hi v17, v37 offset:10640
	ds_write_b16 v17, v38 offset:13440
	ds_write_b16_d16_hi v17, v38 offset:14000
	ds_write_b16 v17, v39 offset:14560
	ds_write_b16_d16_hi v17, v39 offset:15120
	ds_write_b16 v17, v64 offset:2240
	ds_write_b16_d16_hi v17, v64 offset:2800
	ds_write_b16 v17, v65 offset:3360
	ds_write_b16_d16_hi v17, v65 offset:3920
	ds_write_b16 v17, v66 offset:6720
	ds_write_b16_d16_hi v17, v66 offset:7280
	ds_write_b16 v17, v67 offset:7840
	ds_write_b16_d16_hi v17, v67 offset:8400
	ds_write_b16 v17, v68 offset:11200
	ds_write_b16_d16_hi v17, v68 offset:11760
	ds_write_b16 v17, v69 offset:12320
	ds_write_b16_d16_hi v17, v69 offset:12880
	ds_write_b16 v17, v70 offset:15680
	ds_write_b16_d16_hi v17, v70 offset:16240
	ds_write_b16 v17, v71 offset:16800
	ds_write_b16_d16_hi v17, v71 offset:17360
	ds_write_b16 v17, v72 offset:17920
	ds_write_b16_d16_hi v17, v72 offset:18480
	ds_write_b16 v17, v73 offset:19040
	ds_write_b16_d16_hi v17, v73 offset:19600
	ds_write_b16 v17, v74 offset:22400
	ds_write_b16_d16_hi v17, v74 offset:22960
	ds_write_b16 v17, v75 offset:23520
	ds_write_b16_d16_hi v17, v75 offset:24080
	ds_write_b16 v17, v76 offset:26880
	ds_write_b16_d16_hi v17, v76 offset:27440
	ds_write_b16 v17, v77 offset:28000
	ds_write_b16_d16_hi v17, v77 offset:28560
	ds_write_b16 v17, v78 offset:31360
	ds_write_b16_d16_hi v17, v78 offset:31920
	ds_write_b16 v17, v79 offset:32480
	ds_write_b16_d16_hi v17, v79 offset:33040
	ds_write_b16 v17, v80 offset:20160
	ds_write_b16_d16_hi v17, v80 offset:20720
	ds_write_b16 v17, v81 offset:21280
	ds_write_b16_d16_hi v17, v81 offset:21840
	ds_write_b16 v17, v82 offset:24640
	ds_write_b16_d16_hi v17, v82 offset:25200
	ds_write_b16 v17, v83 offset:25760
	ds_write_b16_d16_hi v17, v83 offset:26320
	ds_write_b16 v17, v84 offset:29120
	ds_write_b16_d16_hi v17, v84 offset:29680
	ds_write_b16 v17, v85 offset:30240
	ds_write_b16_d16_hi v17, v85 offset:30800
	ds_write_b16 v17, v86 offset:33600
	ds_write_b16_d16_hi v17, v86 offset:34160
	ds_write_b16 v17, v87 offset:34720
	ds_write_b16_d16_hi v17, v87 offset:35280
	v_add_u32_e32 v66, 0x8c18, v119
	v_add_u32_e32 v64, 0x8c40, v119
	v_add_u32_e32 v65, 0x8c48, v119
	v_add_u32_e32 v67, 0x8c50, v119
	v_add_u32_e32 v86, 0x8c58, v119
	v_add_u32_e32 v82, 0x8c80, v119
	v_add_u32_e32 v78, 0x8c88, v119
	v_add_u32_e32 v74, 0x8c90, v119
	v_add_u32_e32 v46, 0x8c98, v119
	v_add_u32_e32 v47, 0x8cc0, v119
	v_add_u32_e32 v38, 0x8cc8, v119
	v_add_u32_e32 v34, 0x8cd0, v119
	v_lshlrev_b32_e32 v102, 16, v54
	v_and_b32_e32 v103, 0xffff0000, v54
	v_add_f32_e32 v52, v142, v52
	s_waitcnt lgkmcnt(0)
	s_barrier
	ds_read2_b32 v[34:35], v34 offset1:1
	ds_read2_b32 v[38:39], v38 offset1:1
	ds_read2_b32 v[98:99], v64 offset1:1
	v_lshlrev_b32_e32 v36, 16, v43
	v_and_b32_e32 v37, 0xffff0000, v43
	v_lshlrev_b32_e32 v40, 16, v42
	v_and_b32_e32 v41, 0xffff0000, v42
	ds_read2_b32 v[42:43], v47 offset1:1
	ds_read2_b32 v[74:75], v74 offset1:1
	ds_read2_b32 v[94:95], v65 offset1:1
	ds_read2_b32 v[78:79], v78 offset1:1
	ds_read2_b32 v[82:83], v82 offset1:1
	ds_read2_b32 v[86:87], v86 offset1:1
	ds_read2_b32 v[90:91], v67 offset1:1
	v_lshlrev_b32_e32 v64, 16, v55
	ds_read2_b32 v[66:67], v66 offset1:1
	ds_read2_b32 v[46:47], v46 offset1:1
	v_and_b32_e32 v65, 0xffff0000, v55
	v_pk_mul_f32 v[54:55], v[102:103], v[102:103]
	v_add_f32_e32 v52, v143, v52
	v_add_f32_e32 v52, v54, v52
	v_pk_mul_f32 v[140:141], v[64:65], v[64:65]
	v_add_f32_e32 v52, v55, v52
	v_lshlrev_b32_e32 v96, 16, v56
	v_and_b32_e32 v97, 0xffff0000, v56
	v_add_f32_e32 v52, v140, v52
	v_lshlrev_b32_e32 v92, 16, v57
	v_and_b32_e32 v93, 0xffff0000, v57
	v_pk_mul_f32 v[56:57], v[96:97], v[96:97]
	v_add_f32_e32 v52, v141, v52
	v_add_f32_e32 v52, v56, v52
	v_pk_mul_f32 v[134:135], v[92:93], v[92:93]
	v_add_f32_e32 v52, v57, v52
	v_lshlrev_b32_e32 v88, 16, v58
	v_and_b32_e32 v89, 0xffff0000, v58
	v_add_f32_e32 v52, v134, v52
	v_lshlrev_b32_e32 v84, 16, v59
	v_and_b32_e32 v85, 0xffff0000, v59
	v_pk_mul_f32 v[58:59], v[88:89], v[88:89]
	v_add_f32_e32 v52, v135, v52
	v_add_f32_e32 v52, v58, v52
	v_pk_mul_f32 v[132:133], v[84:85], v[84:85]
	v_add_f32_e32 v52, v59, v52
	v_lshlrev_b32_e32 v80, 16, v60
	v_and_b32_e32 v81, 0xffff0000, v60
	v_add_f32_e32 v52, v132, v52
	v_lshlrev_b32_e32 v76, 16, v61
	v_and_b32_e32 v77, 0xffff0000, v61
	v_pk_mul_f32 v[60:61], v[80:81], v[80:81]
	v_add_f32_e32 v52, v133, v52
	v_add_f32_e32 v52, v60, v52
	v_pk_mul_f32 v[130:131], v[76:77], v[76:77]
	v_add_f32_e32 v52, v61, v52
	v_lshlrev_b32_e32 v17, 2, v117
	v_lshlrev_b32_e32 v72, 16, v62
	v_and_b32_e32 v73, 0xffff0000, v62
	v_add_f32_e32 v52, v130, v52
	v_xor_b32_e32 v126, 0x80, v17
	v_lshlrev_b32_e32 v16, 16, v45
	v_and_b32_e32 v17, 0xffff0000, v45
	v_lshlrev_b32_e32 v32, 16, v44
	v_and_b32_e32 v33, 0xffff0000, v44
	v_lshlrev_b32_e32 v44, 16, v63
	v_and_b32_e32 v45, 0xffff0000, v63
	v_pk_mul_f32 v[62:63], v[72:73], v[72:73]
	v_add_f32_e32 v52, v131, v52
	v_add_f32_e32 v52, v62, v52
	v_pk_mul_f32 v[128:129], v[44:45], v[44:45]
	v_add_f32_e32 v52, v63, v52
	v_add_f32_e32 v52, v128, v52
	v_pk_mul_f32 v[120:121], v[40:41], v[40:41]
	v_add_f32_e32 v52, v129, v52
	v_add_f32_e32 v52, v120, v52
	v_pk_mul_f32 v[112:113], v[36:37], v[36:37]
	v_add_f32_e32 v52, v121, v52
	v_add_f32_e32 v52, v112, v52
	v_pk_mul_f32 v[70:71], v[32:33], v[32:33]
	v_add_f32_e32 v52, v113, v52
	v_add_f32_e32 v52, v70, v52
	v_pk_mul_f32 v[68:69], v[16:17], v[16:17]
	v_add_f32_e32 v52, v71, v52
	v_add_f32_e32 v52, v68, v52
	v_add_u32_e32 v108, 0x8c00, v119
	v_add_u32_e32 v104, 0x8c08, v119
	v_add_u32_e32 v100, 0x8c10, v119
	v_add_u32_e32 v127, 0x8cd8, v119
	v_add_f32_e32 v120, v69, v52
	ds_read2_b32 v[100:101], v100 offset1:1
	ds_read2_b32 v[104:105], v104 offset1:1
	ds_read2_b32 v[108:109], v108 offset1:1
	ds_read2_b32 v[112:113], v127 offset1:1
	ds_bpermute_b32 v121, v126, v120
	s_sub_i32 s10, s0, 64
	s_movk_i32 s0, 0x7f
	v_cmp_lt_u32_e32 vcc, s0, v114
	s_or_b64 s[92:93], s[6:7], vcc
	s_and_saveexec_b64 s[0:1], s[92:93]
	s_cbranch_execz .LBB0_400
	v_add_u32_e32 v52, s10, v125
	v_or_b32_e32 v53, v52, v124
	v_cmp_lt_i32_e32 vcc, -1, v52
	s_nop 1
	v_cndmask_b32_e32 v52, 0, v53, vcc
	v_ashrrev_i32_e32 v53, 31, v52
	v_lshlrev_b64 v[52:53], 7, v[52:53]
	v_lshl_add_u64 v[68:69], v[30:31], 0, v[52:53]
	global_load_dwordx4 v[52:55], v[68:69], off
	global_load_dwordx4 v[56:59], v[68:69], off offset:32
	global_load_dwordx4 v[60:63], v[68:69], off offset:64
	s_nop 0
	global_load_dwordx4 v[68:71], v[68:69], off offset:96
